# transpose_item gain folding (w_out): 16 serialized gain loads batched behind one wait (4 sites); + state-item load batching, branch-free ssd_out, attention stagger, ssd1 remap
# baseline (speedup 1.0000x reference)
.LBB0_241:
	s_andn2_b64 vcc, exec, s[6:7]
	s_cbranch_vccnz .LBB0_276
	s_add_i32 s0, s58, 0x1400
	v_mov_b32_e32 v21, v164
	s_and_b32 s1, s0, 0x7fffffc0
	s_add_i32 s0, s56, 0xffff55e0
	s_and_b32 s0, s0, 0x3c0
	v_and_b32_e32 v22, 63, v21
	v_bfe_u32 v23, v21, 6, 2
	v_or_b32_e32 v0, s0, v22
	v_or_b32_e32 v30, s1, v23
	v_lshlrev_b32_e32 v16, 2, v0
	v_lshl_add_u64 v[8:9], s[26:27], 0, v[16:17]
	v_mov_b32_e32 v16, v30
	v_or_b32_e32 v2, 4, v30
	v_mov_b32_e32 v3, v17
	v_or_b32_e32 v4, 8, v30
	v_mov_b32_e32 v5, v17
	v_or_b32_e32 v6, 12, v30
	v_mov_b32_e32 v7, v17
	v_or_b32_e32 v10, 16, v30
	v_mov_b32_e32 v11, v17
	v_or_b32_e32 v12, 20, v30
	v_mov_b32_e32 v13, v17
	v_or_b32_e32 v14, 24, v30
	v_mov_b32_e32 v15, v17
	v_lshlrev_b64 v[0:1], 12, v[16:17]
	v_lshlrev_b64 v[2:3], 12, v[2:3]
	v_lshlrev_b64 v[4:5], 12, v[4:5]
	v_lshlrev_b64 v[6:7], 12, v[6:7]
	v_lshlrev_b64 v[10:11], 12, v[10:11]
	v_lshlrev_b64 v[12:13], 12, v[12:13]
	v_lshlrev_b64 v[14:15], 12, v[14:15]
	v_or_b32_e32 v18, 28, v30
	v_mov_b32_e32 v19, v17
	v_lshl_add_u64 v[0:1], v[8:9], 0, v[0:1]
	v_lshl_add_u64 v[2:3], v[8:9], 0, v[2:3]
	v_lshl_add_u64 v[4:5], v[8:9], 0, v[4:5]
	v_lshl_add_u64 v[6:7], v[8:9], 0, v[6:7]
	v_lshl_add_u64 v[10:11], v[8:9], 0, v[10:11]
	v_lshl_add_u64 v[12:13], v[8:9], 0, v[12:13]
	v_lshl_add_u64 v[14:15], v[8:9], 0, v[14:15]
	v_lshlrev_b64 v[18:19], 12, v[18:19]
	v_lshl_add_u64 v[18:19], v[8:9], 0, v[18:19]
	global_load_dword v0, v[0:1], off
	s_nop 0
	global_load_dword v1, v[2:3], off
	s_nop 0
	global_load_dword v2, v[4:5], off
	global_load_dword v3, v[6:7], off
	s_nop 0
	global_load_dword v4, v[10:11], off
	global_load_dword v5, v[12:13], off
	global_load_dword v6, v[14:15], off
	global_load_dword v7, v[18:19], off
	v_or_b32_e32 v10, 32, v30
	v_mov_b32_e32 v11, v17
	v_or_b32_e32 v12, 36, v30
	v_mov_b32_e32 v13, v17
	v_or_b32_e32 v14, 40, v30
	v_mov_b32_e32 v15, v17
	v_lshlrev_b64 v[10:11], 12, v[10:11]
	v_lshlrev_b64 v[12:13], 12, v[12:13]
	v_lshlrev_b64 v[14:15], 12, v[14:15]
	v_or_b32_e32 v18, 44, v30
	v_mov_b32_e32 v19, v17
	v_or_b32_e32 v24, 48, v30
	v_mov_b32_e32 v25, v17
	v_or_b32_e32 v26, 52, v30
	v_mov_b32_e32 v27, v17
	v_or_b32_e32 v28, 56, v30
	v_mov_b32_e32 v29, v17
	v_or_b32_e32 v30, 60, v30
	v_mov_b32_e32 v31, v17
	v_lshl_add_u64 v[10:11], v[8:9], 0, v[10:11]
	v_lshl_add_u64 v[12:13], v[8:9], 0, v[12:13]
	v_lshl_add_u64 v[14:15], v[8:9], 0, v[14:15]
	v_lshlrev_b64 v[18:19], 12, v[18:19]
	v_lshlrev_b64 v[24:25], 12, v[24:25]
	v_lshlrev_b64 v[26:27], 12, v[26:27]
	v_lshlrev_b64 v[28:29], 12, v[28:29]
	v_lshlrev_b64 v[30:31], 12, v[30:31]
	v_lshl_add_u64 v[18:19], v[8:9], 0, v[18:19]
	v_lshl_add_u64 v[24:25], v[8:9], 0, v[24:25]
	v_lshl_add_u64 v[26:27], v[8:9], 0, v[26:27]
	v_lshl_add_u64 v[28:29], v[8:9], 0, v[28:29]
	v_lshl_add_u64 v[30:31], v[8:9], 0, v[30:31]
	global_load_dword v8, v[10:11], off
	global_load_dword v9, v[12:13], off
	s_nop 0
	global_load_dword v10, v[14:15], off
	global_load_dword v11, v[18:19], off
	global_load_dword v12, v[24:25], off
	global_load_dword v13, v[26:27], off
	s_nop 0
	global_load_dword v14, v[28:29], off
	global_load_dword v15, v[30:31], off
	s_and_b64 vcc, exec, s[4:5]
	s_cbranch_vccnz .LBB0_275
	s_add_i32 s2, s45, 0xfffffd58
	s_cmpk_gt_u32 s2, 0x7f
	s_cselect_b64 s[38:39], -1, 0
	s_cmpk_lt_u32 s2, 0x80
	v_lshl_add_u64 v[18:19], v[16:17], 2, s[24:25]
	s_cbranch_scc1 .LBB0_259
	global_load_dword v32, v[18:19], off offset:-2048
	global_load_dword v33, v[18:19], off offset:-2032
	global_load_dword v34, v[18:19], off offset:-2016
	global_load_dword v35, v[18:19], off offset:-2000
	global_load_dword v36, v[18:19], off offset:-1984
	global_load_dword v37, v[18:19], off offset:-1968
	global_load_dword v38, v[18:19], off offset:-1952
	global_load_dword v39, v[18:19], off offset:-1936
	global_load_dword v40, v[18:19], off offset:-1920
	global_load_dword v41, v[18:19], off offset:-1904
	global_load_dword v42, v[18:19], off offset:-1888
	global_load_dword v43, v[18:19], off offset:-1872
	global_load_dword v44, v[18:19], off offset:-1856
	global_load_dword v45, v[18:19], off offset:-1840
	global_load_dword v46, v[18:19], off offset:-1824
	global_load_dword v47, v[18:19], off offset:-1808
	s_waitcnt vmcnt(0)
	v_mul_f32_e32 v0, v0, v32
	v_mul_f32_e32 v1, v1, v33
	v_mul_f32_e32 v2, v2, v34
	v_mul_f32_e32 v3, v3, v35
	v_mul_f32_e32 v4, v4, v36
	v_mul_f32_e32 v5, v5, v37
	v_mul_f32_e32 v6, v6, v38
	v_mul_f32_e32 v7, v7, v39
	v_mul_f32_e32 v8, v8, v40
	v_mul_f32_e32 v9, v9, v41
	v_mul_f32_e32 v10, v10, v42
	v_mul_f32_e32 v11, v11, v43
	v_mul_f32_e32 v12, v12, v44
	v_mul_f32_e32 v13, v13, v45
	v_mul_f32_e32 v14, v14, v46
	v_mul_f32_e32 v15, v15, v47
	s_branch .LBB0_275
	v_cndmask_b32_e64 v16, 0, 1, s[38:39]
	v_cmp_ne_u32_e64 s[6:7], 1, v16
	s_andn2_b64 vcc, exec, s[38:39]
	s_cbranch_vccz .LBB0_260

.LBB0_336:
	s_andn2_b64 vcc, exec, s[4:5]
	s_cbranch_vccnz .LBB0_371
	s_add_i32 s0, s56, 0xfffffa20
	v_mov_b32_e32 v21, v164
	s_and_b32 s1, s0, 0x7fffffc0
	s_add_i32 s0, s55, 0xffffa200
	s_and_b32 s0, s0, 0x3c0
	v_and_b32_e32 v22, 63, v21
	v_bfe_u32 v23, v21, 6, 2
	v_or_b32_e32 v0, s0, v22
	v_or_b32_e32 v30, s1, v23
	v_lshlrev_b32_e32 v16, 2, v0
	v_lshl_add_u64 v[8:9], s[26:27], 0, v[16:17]
	v_mov_b32_e32 v16, v30
	v_or_b32_e32 v2, 4, v30
	v_mov_b32_e32 v3, v17
	v_or_b32_e32 v4, 8, v30
	v_mov_b32_e32 v5, v17
	v_or_b32_e32 v6, 12, v30
	v_mov_b32_e32 v7, v17
	v_or_b32_e32 v10, 16, v30
	v_mov_b32_e32 v11, v17
	v_or_b32_e32 v12, 20, v30
	v_mov_b32_e32 v13, v17
	v_or_b32_e32 v14, 24, v30
	v_mov_b32_e32 v15, v17
	v_lshlrev_b64 v[0:1], 12, v[16:17]
	v_lshlrev_b64 v[2:3], 12, v[2:3]
	v_lshlrev_b64 v[4:5], 12, v[4:5]
	v_lshlrev_b64 v[6:7], 12, v[6:7]
	v_lshlrev_b64 v[10:11], 12, v[10:11]
	v_lshlrev_b64 v[12:13], 12, v[12:13]
	v_lshlrev_b64 v[14:15], 12, v[14:15]
	v_or_b32_e32 v18, 28, v30
	v_mov_b32_e32 v19, v17
	v_lshl_add_u64 v[0:1], v[8:9], 0, v[0:1]
	v_lshl_add_u64 v[2:3], v[8:9], 0, v[2:3]
	v_lshl_add_u64 v[4:5], v[8:9], 0, v[4:5]
	v_lshl_add_u64 v[6:7], v[8:9], 0, v[6:7]
	v_lshl_add_u64 v[10:11], v[8:9], 0, v[10:11]
	v_lshl_add_u64 v[12:13], v[8:9], 0, v[12:13]
	v_lshl_add_u64 v[14:15], v[8:9], 0, v[14:15]
	v_lshlrev_b64 v[18:19], 12, v[18:19]
	v_lshl_add_u64 v[18:19], v[8:9], 0, v[18:19]
	global_load_dword v0, v[0:1], off
	s_nop 0
	global_load_dword v1, v[2:3], off
	s_nop 0
	global_load_dword v2, v[4:5], off
	global_load_dword v3, v[6:7], off
	s_nop 0
	global_load_dword v4, v[10:11], off
	global_load_dword v5, v[12:13], off
	global_load_dword v6, v[14:15], off
	global_load_dword v7, v[18:19], off
	v_or_b32_e32 v10, 32, v30
	v_mov_b32_e32 v11, v17
	v_or_b32_e32 v12, 36, v30
	v_mov_b32_e32 v13, v17
	v_or_b32_e32 v14, 40, v30
	v_mov_b32_e32 v15, v17
	v_lshlrev_b64 v[10:11], 12, v[10:11]
	v_lshlrev_b64 v[12:13], 12, v[12:13]
	v_lshlrev_b64 v[14:15], 12, v[14:15]
	v_or_b32_e32 v18, 44, v30
	v_mov_b32_e32 v19, v17
	v_or_b32_e32 v24, 48, v30
	v_mov_b32_e32 v25, v17
	v_or_b32_e32 v26, 52, v30
	v_mov_b32_e32 v27, v17
	v_or_b32_e32 v28, 56, v30
	v_mov_b32_e32 v29, v17
	v_or_b32_e32 v30, 60, v30
	v_mov_b32_e32 v31, v17
	v_lshl_add_u64 v[10:11], v[8:9], 0, v[10:11]
	v_lshl_add_u64 v[12:13], v[8:9], 0, v[12:13]
	v_lshl_add_u64 v[14:15], v[8:9], 0, v[14:15]
	v_lshlrev_b64 v[18:19], 12, v[18:19]
	v_lshlrev_b64 v[24:25], 12, v[24:25]
	v_lshlrev_b64 v[26:27], 12, v[26:27]
	v_lshlrev_b64 v[28:29], 12, v[28:29]
	v_lshlrev_b64 v[30:31], 12, v[30:31]
	v_lshl_add_u64 v[18:19], v[8:9], 0, v[18:19]
	v_lshl_add_u64 v[24:25], v[8:9], 0, v[24:25]
	v_lshl_add_u64 v[26:27], v[8:9], 0, v[26:27]
	v_lshl_add_u64 v[28:29], v[8:9], 0, v[28:29]
	v_lshl_add_u64 v[30:31], v[8:9], 0, v[30:31]
	global_load_dword v8, v[10:11], off
	global_load_dword v9, v[12:13], off
	s_nop 0
	global_load_dword v10, v[14:15], off
	global_load_dword v11, v[18:19], off
	global_load_dword v12, v[24:25], off
	global_load_dword v13, v[26:27], off
	s_nop 0
	global_load_dword v14, v[28:29], off
	global_load_dword v15, v[30:31], off
	s_andn2_b64 vcc, exec, s[6:7]
	s_cbranch_vccnz .LBB0_370
	s_add_i32 s2, s57, 0x100
	s_cmpk_gt_u32 s2, 0x7f
	s_cselect_b64 s[38:39], -1, 0
	s_cmpk_lt_u32 s2, 0x80
	v_lshl_add_u64 v[18:19], v[16:17], 2, s[24:25]
	s_cbranch_scc1 .LBB0_354
	global_load_dword v32, v[18:19], off offset:-2048
	global_load_dword v33, v[18:19], off offset:-2032
	global_load_dword v34, v[18:19], off offset:-2016
	global_load_dword v35, v[18:19], off offset:-2000
	global_load_dword v36, v[18:19], off offset:-1984
	global_load_dword v37, v[18:19], off offset:-1968
	global_load_dword v38, v[18:19], off offset:-1952
	global_load_dword v39, v[18:19], off offset:-1936
	global_load_dword v40, v[18:19], off offset:-1920
	global_load_dword v41, v[18:19], off offset:-1904
	global_load_dword v42, v[18:19], off offset:-1888
	global_load_dword v43, v[18:19], off offset:-1872
	global_load_dword v44, v[18:19], off offset:-1856
	global_load_dword v45, v[18:19], off offset:-1840
	global_load_dword v46, v[18:19], off offset:-1824
	global_load_dword v47, v[18:19], off offset:-1808
	s_waitcnt vmcnt(0)
	v_mul_f32_e32 v0, v0, v32
	v_mul_f32_e32 v1, v1, v33
	v_mul_f32_e32 v2, v2, v34
	v_mul_f32_e32 v3, v3, v35
	v_mul_f32_e32 v4, v4, v36
	v_mul_f32_e32 v5, v5, v37
	v_mul_f32_e32 v6, v6, v38
	v_mul_f32_e32 v7, v7, v39
	v_mul_f32_e32 v8, v8, v40
	v_mul_f32_e32 v9, v9, v41
	v_mul_f32_e32 v10, v10, v42
	v_mul_f32_e32 v11, v11, v43
	v_mul_f32_e32 v12, v12, v44
	v_mul_f32_e32 v13, v13, v45
	v_mul_f32_e32 v14, v14, v46
	v_mul_f32_e32 v15, v15, v47
	s_branch .LBB0_370
	v_cndmask_b32_e64 v16, 0, 1, s[38:39]
	v_cmp_ne_u32_e64 s[4:5], 1, v16
	s_andn2_b64 vcc, exec, s[38:39]
	s_cbranch_vccz .LBB0_355

.LBB0_1268:
	s_andn2_b64 vcc, exec, s[4:5]
	s_cbranch_vccnz .LBB0_1303
	s_add_i32 s0, s76, 0x1400
	v_mov_b32_e32 v21, v164
	s_and_b32 s1, s0, 0x7fffffc0
	s_add_i32 s0, s74, 0xffff55e0
	s_and_b32 s0, s0, 0x3c0
	v_and_b32_e32 v22, 63, v21
	v_bfe_u32 v23, v21, 6, 2
	v_or_b32_e32 v0, s0, v22
	v_or_b32_e32 v24, s1, v23
	v_lshlrev_b32_e32 v16, 2, v0
	v_lshl_add_u64 v[18:19], s[34:35], 0, v[16:17]
	v_mov_b32_e32 v16, v24
	v_or_b32_e32 v2, 4, v24
	v_mov_b32_e32 v3, v17
	v_lshlrev_b64 v[0:1], 12, v[16:17]
	v_lshlrev_b64 v[2:3], 12, v[2:3]
	v_lshl_add_u64 v[0:1], v[18:19], 0, v[0:1]
	v_lshl_add_u64 v[2:3], v[18:19], 0, v[2:3]
	global_load_dword v0, v[0:1], off
	v_or_b32_e32 v4, 12, v24
	global_load_dword v1, v[2:3], off
	v_or_b32_e32 v2, 8, v24
	v_mov_b32_e32 v3, v17
	v_mov_b32_e32 v5, v17
	v_lshlrev_b64 v[2:3], 12, v[2:3]
	v_lshlrev_b64 v[4:5], 12, v[4:5]
	v_lshl_add_u64 v[2:3], v[18:19], 0, v[2:3]
	v_lshl_add_u64 v[4:5], v[18:19], 0, v[4:5]
	global_load_dword v2, v[2:3], off
	v_or_b32_e32 v6, 20, v24
	global_load_dword v3, v[4:5], off
	v_or_b32_e32 v4, 16, v24
	v_mov_b32_e32 v5, v17
	v_mov_b32_e32 v7, v17
	v_lshlrev_b64 v[4:5], 12, v[4:5]
	v_lshlrev_b64 v[6:7], 12, v[6:7]
	v_lshl_add_u64 v[4:5], v[18:19], 0, v[4:5]
	v_lshl_add_u64 v[6:7], v[18:19], 0, v[6:7]
	global_load_dword v4, v[4:5], off
	v_or_b32_e32 v8, 28, v24
	global_load_dword v5, v[6:7], off
	v_or_b32_e32 v6, 24, v24
	v_mov_b32_e32 v7, v17
	v_mov_b32_e32 v9, v17
	v_lshlrev_b64 v[6:7], 12, v[6:7]
	v_lshlrev_b64 v[8:9], 12, v[8:9]
	v_lshl_add_u64 v[6:7], v[18:19], 0, v[6:7]
	v_lshl_add_u64 v[8:9], v[18:19], 0, v[8:9]
	global_load_dword v6, v[6:7], off
	v_or_b32_e32 v10, 36, v24
	global_load_dword v7, v[8:9], off
	v_or_b32_e32 v8, 32, v24
	v_mov_b32_e32 v9, v17
	v_mov_b32_e32 v11, v17
	v_lshlrev_b64 v[8:9], 12, v[8:9]
	v_lshlrev_b64 v[10:11], 12, v[10:11]
	v_lshl_add_u64 v[8:9], v[18:19], 0, v[8:9]
	v_lshl_add_u64 v[10:11], v[18:19], 0, v[10:11]
	global_load_dword v8, v[8:9], off
	v_or_b32_e32 v12, 44, v24
	global_load_dword v9, v[10:11], off
	v_or_b32_e32 v10, 40, v24
	v_mov_b32_e32 v11, v17
	v_mov_b32_e32 v13, v17
	v_lshlrev_b64 v[10:11], 12, v[10:11]
	v_lshlrev_b64 v[12:13], 12, v[12:13]
	v_lshl_add_u64 v[10:11], v[18:19], 0, v[10:11]
	v_lshl_add_u64 v[12:13], v[18:19], 0, v[12:13]
	global_load_dword v10, v[10:11], off
	v_or_b32_e32 v14, 52, v24
	global_load_dword v11, v[12:13], off
	v_or_b32_e32 v12, 48, v24
	v_mov_b32_e32 v13, v17
	v_mov_b32_e32 v15, v17
	v_lshlrev_b64 v[12:13], 12, v[12:13]
	v_lshlrev_b64 v[14:15], 12, v[14:15]
	v_lshl_add_u64 v[12:13], v[18:19], 0, v[12:13]
	v_lshl_add_u64 v[14:15], v[18:19], 0, v[14:15]
	global_load_dword v12, v[12:13], off
	v_mov_b32_e32 v25, v17
	global_load_dword v13, v[14:15], off
	v_or_b32_e32 v14, 56, v24
	v_mov_b32_e32 v15, v17
	v_or_b32_e32 v24, 60, v24
	v_lshlrev_b64 v[14:15], 12, v[14:15]
	v_lshlrev_b64 v[24:25], 12, v[24:25]
	v_lshl_add_u64 v[14:15], v[18:19], 0, v[14:15]
	v_lshl_add_u64 v[18:19], v[18:19], 0, v[24:25]
	global_load_dword v14, v[14:15], off
	s_andn2_b64 vcc, exec, s[36:37]
	global_load_dword v15, v[18:19], off
	s_cbranch_vccnz .LBB0_1302
	s_add_i32 s2, s83, 0xfffffd58
	s_cmpk_gt_u32 s2, 0x7f
	s_cselect_b64 s[66:67], -1, 0
	s_cmpk_lt_u32 s2, 0x80
	v_lshl_add_u64 v[18:19], v[16:17], 2, s[18:19]
	s_cbranch_scc1 .LBB0_1286
	global_load_dword v32, v[18:19], off
	global_load_dword v33, v[18:19], off offset:16
	global_load_dword v34, v[18:19], off offset:32
	global_load_dword v35, v[18:19], off offset:48
	global_load_dword v36, v[18:19], off offset:64
	global_load_dword v37, v[18:19], off offset:80
	global_load_dword v38, v[18:19], off offset:96
	global_load_dword v39, v[18:19], off offset:112
	global_load_dword v40, v[18:19], off offset:128
	global_load_dword v41, v[18:19], off offset:144
	global_load_dword v42, v[18:19], off offset:160
	global_load_dword v43, v[18:19], off offset:176
	global_load_dword v44, v[18:19], off offset:192
	global_load_dword v45, v[18:19], off offset:208
	global_load_dword v46, v[18:19], off offset:224
	global_load_dword v47, v[18:19], off offset:240
	s_waitcnt vmcnt(0)
	v_mul_f32_e32 v0, v0, v32
	v_mul_f32_e32 v1, v1, v33
	v_mul_f32_e32 v2, v2, v34
	v_mul_f32_e32 v3, v3, v35
	v_mul_f32_e32 v4, v4, v36
	v_mul_f32_e32 v5, v5, v37
	v_mul_f32_e32 v6, v6, v38
	v_mul_f32_e32 v7, v7, v39
	v_mul_f32_e32 v8, v8, v40
	v_mul_f32_e32 v9, v9, v41
	v_mul_f32_e32 v10, v10, v42
	v_mul_f32_e32 v11, v11, v43
	v_mul_f32_e32 v12, v12, v44
	v_mul_f32_e32 v13, v13, v45
	v_mul_f32_e32 v14, v14, v46
	v_mul_f32_e32 v15, v15, v47
	s_branch .LBB0_1302
	v_cndmask_b32_e64 v16, 0, 1, s[66:67]
	v_cmp_ne_u32_e64 s[4:5], 1, v16
	s_andn2_b64 vcc, exec, s[66:67]
	s_cbranch_vccz .LBB0_1287

.LBB0_1362:
	s_andn2_b64 vcc, exec, s[4:5]
	s_cbranch_vccnz .LBB0_1397
	s_add_i32 s0, s61, 0x1400
	v_mov_b32_e32 v21, v164
	s_and_b32 s1, s0, 0x7fffffc0
	s_add_i32 s0, s60, 0x14000
	s_and_b32 s0, s0, 0x3c0
	v_and_b32_e32 v22, 63, v21
	v_bfe_u32 v23, v21, 6, 2
	v_or_b32_e32 v0, s0, v22
	v_or_b32_e32 v30, s1, v23
	v_lshlrev_b32_e32 v16, 2, v0
	v_lshl_add_u64 v[8:9], s[26:27], 0, v[16:17]
	v_mov_b32_e32 v16, v30
	v_or_b32_e32 v2, 4, v30
	v_mov_b32_e32 v3, v17
	v_or_b32_e32 v4, 8, v30
	v_mov_b32_e32 v5, v17
	v_or_b32_e32 v6, 12, v30
	v_mov_b32_e32 v7, v17
	v_or_b32_e32 v10, 16, v30
	v_mov_b32_e32 v11, v17
	v_or_b32_e32 v12, 20, v30
	v_mov_b32_e32 v13, v17
	v_or_b32_e32 v14, 24, v30
	v_mov_b32_e32 v15, v17
	v_lshlrev_b64 v[0:1], 12, v[16:17]
	v_lshlrev_b64 v[2:3], 12, v[2:3]
	v_lshlrev_b64 v[4:5], 12, v[4:5]
	v_lshlrev_b64 v[6:7], 12, v[6:7]
	v_lshlrev_b64 v[10:11], 12, v[10:11]
	v_lshlrev_b64 v[12:13], 12, v[12:13]
	v_lshlrev_b64 v[14:15], 12, v[14:15]
	v_or_b32_e32 v18, 28, v30
	v_mov_b32_e32 v19, v17
	v_lshl_add_u64 v[0:1], v[8:9], 0, v[0:1]
	v_lshl_add_u64 v[2:3], v[8:9], 0, v[2:3]
	v_lshl_add_u64 v[4:5], v[8:9], 0, v[4:5]
	v_lshl_add_u64 v[6:7], v[8:9], 0, v[6:7]
	v_lshl_add_u64 v[10:11], v[8:9], 0, v[10:11]
	v_lshl_add_u64 v[12:13], v[8:9], 0, v[12:13]
	v_lshl_add_u64 v[14:15], v[8:9], 0, v[14:15]
	v_lshlrev_b64 v[18:19], 12, v[18:19]
	v_lshl_add_u64 v[18:19], v[8:9], 0, v[18:19]
	global_load_dword v0, v[0:1], off
	s_nop 0
	global_load_dword v1, v[2:3], off
	s_nop 0
	global_load_dword v2, v[4:5], off
	global_load_dword v3, v[6:7], off
	s_nop 0
	global_load_dword v4, v[10:11], off
	global_load_dword v5, v[12:13], off
	global_load_dword v6, v[14:15], off
	global_load_dword v7, v[18:19], off
	v_or_b32_e32 v10, 32, v30
	v_mov_b32_e32 v11, v17
	v_or_b32_e32 v12, 36, v30
	v_mov_b32_e32 v13, v17
	v_or_b32_e32 v14, 40, v30
	v_mov_b32_e32 v15, v17
	v_lshlrev_b64 v[10:11], 12, v[10:11]
	v_lshlrev_b64 v[12:13], 12, v[12:13]
	v_lshlrev_b64 v[14:15], 12, v[14:15]
	v_or_b32_e32 v18, 44, v30
	v_mov_b32_e32 v19, v17
	v_or_b32_e32 v24, 48, v30
	v_mov_b32_e32 v25, v17
	v_or_b32_e32 v26, 52, v30
	v_mov_b32_e32 v27, v17
	v_or_b32_e32 v28, 56, v30
	v_mov_b32_e32 v29, v17
	v_or_b32_e32 v30, 60, v30
	v_mov_b32_e32 v31, v17
	v_lshl_add_u64 v[10:11], v[8:9], 0, v[10:11]
	v_lshl_add_u64 v[12:13], v[8:9], 0, v[12:13]
	v_lshl_add_u64 v[14:15], v[8:9], 0, v[14:15]
	v_lshlrev_b64 v[18:19], 12, v[18:19]
	v_lshlrev_b64 v[24:25], 12, v[24:25]
	v_lshlrev_b64 v[26:27], 12, v[26:27]
	v_lshlrev_b64 v[28:29], 12, v[28:29]
	v_lshlrev_b64 v[30:31], 12, v[30:31]
	v_lshl_add_u64 v[18:19], v[8:9], 0, v[18:19]
	v_lshl_add_u64 v[24:25], v[8:9], 0, v[24:25]
	v_lshl_add_u64 v[26:27], v[8:9], 0, v[26:27]
	v_lshl_add_u64 v[28:29], v[8:9], 0, v[28:29]
	v_lshl_add_u64 v[30:31], v[8:9], 0, v[30:31]
	global_load_dword v8, v[10:11], off
	global_load_dword v9, v[12:13], off
	s_nop 0
	global_load_dword v10, v[14:15], off
	global_load_dword v11, v[18:19], off
	global_load_dword v12, v[24:25], off
	global_load_dword v13, v[26:27], off
	s_nop 0
	global_load_dword v14, v[28:29], off
	global_load_dword v15, v[30:31], off
	s_andn2_b64 vcc, exec, s[28:29]
	s_cbranch_vccnz .LBB0_1396
	s_add_i32 s2, s38, 0xfffffd58
	s_cmpk_gt_u32 s2, 0x7f
	s_cselect_b64 s[36:37], -1, 0
	s_cmpk_lt_u32 s2, 0x80
	v_lshl_add_u64 v[18:19], v[16:17], 2, s[18:19]
	s_cbranch_scc1 .LBB0_1380
	global_load_dword v32, v[18:19], off
	global_load_dword v33, v[18:19], off offset:16
	global_load_dword v34, v[18:19], off offset:32
	global_load_dword v35, v[18:19], off offset:48
	global_load_dword v36, v[18:19], off offset:64
	global_load_dword v37, v[18:19], off offset:80
	global_load_dword v38, v[18:19], off offset:96
	global_load_dword v39, v[18:19], off offset:112
	global_load_dword v40, v[18:19], off offset:128
	global_load_dword v41, v[18:19], off offset:144
	global_load_dword v42, v[18:19], off offset:160
	global_load_dword v43, v[18:19], off offset:176
	global_load_dword v44, v[18:19], off offset:192
	global_load_dword v45, v[18:19], off offset:208
	global_load_dword v46, v[18:19], off offset:224
	global_load_dword v47, v[18:19], off offset:240
	s_waitcnt vmcnt(0)
	v_mul_f32_e32 v0, v0, v32
	v_mul_f32_e32 v1, v1, v33
	v_mul_f32_e32 v2, v2, v34
	v_mul_f32_e32 v3, v3, v35
	v_mul_f32_e32 v4, v4, v36
	v_mul_f32_e32 v5, v5, v37
	v_mul_f32_e32 v6, v6, v38
	v_mul_f32_e32 v7, v7, v39
	v_mul_f32_e32 v8, v8, v40
	v_mul_f32_e32 v9, v9, v41
	v_mul_f32_e32 v10, v10, v42
	v_mul_f32_e32 v11, v11, v43
	v_mul_f32_e32 v12, v12, v44
	v_mul_f32_e32 v13, v13, v45
	v_mul_f32_e32 v14, v14, v46
	v_mul_f32_e32 v15, v15, v47
	s_branch .LBB0_1396
	v_cndmask_b32_e64 v16, 0, 1, s[36:37]
	v_cmp_ne_u32_e64 s[4:5], 1, v16
	s_andn2_b64 vcc, exec, s[36:37]
	s_cbranch_vccz .LBB0_1381
